# v67: v66 with the post-UP invalidate executed by every workgroup (provably safe inv set {0,1,2,4,7}) and issued early at arrival like the others
# baseline (speedup 1.0000x reference)
; __device__ __forceinline__ unsigned xb_ld(unsigned* p)              { return __hip_atomic_load(p, __ATOMIC_RELAXED, __HIP_MEMORY_SCOPE_AGENT); }
; __device__ __forceinline__ unsigned xb_add(unsigned* p, unsigned v) { return __hip_atomic_fetch_add(p, v, __ATOMIC_RELAXED, __HIP_MEMORY_SCOPE_AGENT); }
; #define XB_SPIN(cond, bar) do { unsigned _sp = 0; while (cond) { __builtin_amdgcn_s_sleep(1); \
;     if ((++_sp & 255u) == 0u) { if (xb_ld(&(bar)[XB_TMO])) break; if (_sp > XB_SPIN_CAP) { atomicAdd(&(bar)[XB_TMO], 1u); break; } } } } while (0)
; __device__ __forceinline__ void xcd_barrier(const XcdBarrier& b) {
;     ...
;     if (threadIdx.x == 0) {
;         unsigned* bar = b.bar;
;         __builtin_amdgcn_s_waitcnt(0);
;         unsigned nloc = b.st[0], nx = b.st[1];
;         if (nloc == 0u) { xcd_barrier_complete(bar, b.x, nloc, nx); b.st[0] = nloc; b.st[1] = nx; }
;         const unsigned old = xb_add(&bar[XB_XSUB(b.x)], 1u);
;         const unsigned gen = old / nloc;
;         if (old + 1u == (gen + 1u) * nloc) {
;             __builtin_amdgcn_fence(__ATOMIC_RELEASE, "agent");
;             asm volatile("s_waitcnt vmcnt(0)" ::: "memory");
;             const unsigned og = xb_add(&bar[XB_TOP], 1u);
;             const unsigned tg = og / nx;
;             if (og + 1u == (tg + 1u) * nx) xb_add(&bar[XB_TOPGEN], 1u);
;             else XB_SPIN(xb_ld(&bar[XB_TOPGEN]) == tg, bar);
;             __builtin_amdgcn_fence(__ATOMIC_ACQUIRE, "agent");
;             xb_add(&bar[XB_XGEN(b.x)], 1u);
;             asm volatile("s_waitcnt vmcnt(0)" ::: "memory");
;         } else {
;             XB_SPIN(xb_ld(&bar[XB_XGEN(b.x)]) == gen, bar);
;             __builtin_amdgcn_fence(__ATOMIC_ACQUIRE, "agent");
;             asm volatile("s_waitcnt vmcnt(0)" ::: "memory");
;         }
.LBB0_1119:
	v_mov_b32_e32 v4, 0x20000
	ds_read2_b32 v[2:3], v4 offset1:1
	v_readlane_b32 s3, v244, 30
	s_nop 0
	s_lshl_b32 s3, s3, 8
	s_getpc_b64 s[8:9]
	s_add_u32 s8, s8, g_xbar@rel32@lo+4
	s_addc_u32 s9, s9, g_xbar@rel32@hi+12
	s_add_u32 s8, s8, s3
	s_addc_u32 s9, s9, 0
	v_mov_b32_e32 v5, 0x1000
	v_mov_b32_e32 v6, 1
	global_atomic_add v5, v5, v6, s[8:9] offset:1024 sc0
	s_movk_i32 s3, 8
	s_waitcnt lgkmcnt(0)
	v_mul_lo_u32 v2, v2, s3
	v_mul_lo_u32 v3, v3, s3
	s_waitcnt vmcnt(0)
	buffer_inv sc1
	v_add_u32_e32 v5, 1, v5
	v_cmp_ne_u32_e32 vcc, v5, v2
	s_getpc_b64 s[8:9]
	s_add_u32 s8, s8, g_xbar@rel32@lo+13316
	s_addc_u32 s9, s9, g_xbar@rel32@hi+13324
	v_mov_b32_e32 v4, 0
	s_cbranch_vccnz .Lfb7_spin0
	buffer_wbl2 sc1
	s_waitcnt vmcnt(0) lgkmcnt(0)
	global_atomic_add v4, v6, s[8:9]
